# pool/conv unit: 4 serializing vmcnt(0) in the load phase removed (wave-uniform if/else register reuse); all 14 tile loads + taps in flight together
# baseline (speedup 1.0000x reference)
.LBB0_1164:
.LBB0_1165:
	s_andn2_saveexec_b64 s[48:49], s[48:49]
	s_cbranch_execz .LBB0_1167
	v_ashrrev_i32_e32 v11, 31, v10
	v_lshl_add_u64 v[2:3], v[10:11], 0, s[28:29]
	v_lshlrev_b64 v[2:3], 10, v[2:3]
	v_lshl_add_u64 v[2:3], v[62:63], 0, v[2:3]
	global_load_dwordx4 v[2:5], v[2:3], off

.LBB0_1180:
.LBB0_1181:
	s_andn2_saveexec_b64 s[52:53], s[52:53]
	s_cbranch_execz .LBB0_1183
	v_ashrrev_i32_e32 v19, 31, v18
	v_lshl_add_u64 v[10:11], v[18:19], 0, s[28:29]
	v_lshlrev_b64 v[10:11], 10, v[10:11]
	v_lshl_add_u64 v[10:11], v[62:63], 0, v[10:11]
	global_load_dwordx4 v[10:13], v[10:11], off

.LBB0_1196:
.LBB0_1197:
	s_andn2_saveexec_b64 s[56:57], s[56:57]
	s_cbranch_execz .LBB0_1199
	v_ashrrev_i32_e32 v27, 31, v26
	v_lshl_add_u64 v[18:19], v[26:27], 0, s[28:29]
	v_lshlrev_b64 v[18:19], 10, v[18:19]
	v_lshl_add_u64 v[18:19], v[62:63], 0, v[18:19]
	global_load_dwordx4 v[18:21], v[18:19], off

.LBB0_1212:
.LBB0_1213:
	s_andn2_saveexec_b64 s[74:75], s[88:89]
	s_cbranch_execz .LBB0_1215
	v_ashrrev_i32_e32 v65, 31, v64
	v_lshl_add_u64 v[26:27], v[64:65], 0, s[28:29]
	v_lshlrev_b64 v[26:27], 10, v[26:27]
	v_lshl_add_u64 v[26:27], v[62:63], 0, v[26:27]
	global_load_dwordx4 v[26:29], v[26:27], off
